# v34 plus prep adaLN GEMV loop: 8 weight-row loads in flight per block with counted vmcnt waits (was one load per trip with vmcnt(0))
# baseline (speedup 1.0000x reference)
; __device__ __forceinline__ void prep_phase(const Params& p, unsigned char* lds_g) {
;     ...
;             const int l = u >> 6, j0 = (u & 63) * 96;
;             if (tid < 504) { const int kg = tid / 24, cq = tid % 24;
;                 f32x4 al = {0.f, 0.f, 0.f, 0.f}, ac = {0.f, 0.f, 0.f, 0.f};
;                 const float* wp = p.in[I_WMOD] + (size_t)l * DM * 6144 + j0 + cq * 4;
;                 for (int k = kg; k < 2048; k += 21) { const f32x4 w = *(const f32x4*)(wp + (size_t)k * 6144); al += sc[k] * w; ac += sc[2048 + k] * w; }
;                 float* rp = red + (kg * 24 + cq) * 8;
;                 rp[0] = al[0]; rp[1] = al[1]; rp[2] = al[2]; rp[3] = al[3]; rp[4] = ac[0]; rp[5] = ac[1]; rp[6] = ac[2]; rp[7] = ac[3]; }
.LBB0_36:
	s_or_b64 exec, exec, s[20:21]
	s_ashr_i32 s30, s29, 6
	s_waitcnt lgkmcnt(0)
	s_barrier
	s_and_saveexec_b64 s[20:21], s[0:1]
	s_cbranch_execz .LBB0_40
	s_and_b32 s8, s28, 63
	s_mulk_i32 s8, 0x180
	s_mul_i32 s10, s30, 0x3000000
	s_mul_hi_i32 s9, s30, 0x3000000
	s_or_b32 s8, s10, s8
	v_mov_b32_e32 v2, 0
	v_lshl_add_u64 v[20:21], v[14:15], 0, s[8:9]
	s_mov_b64 s[22:23], 0
	v_mov_b32_e32 v16, v25
	v_mov_b32_e32 v28, v24
	v_mov_b32_e32 v3, v2
	v_mov_b32_e32 v4, v2
	v_mov_b32_e32 v5, v2
	v_mov_b32_e32 v6, v2
	v_mov_b32_e32 v7, v2
	v_mov_b32_e32 v8, v2
	v_mov_b32_e32 v9, v2
	s_mov_b32 s10, 12
.Lgemv_blk:
	global_load_dwordx4 v[30:33], v[20:21], off
	v_lshl_add_u64 v[20:21], v[20:21], 0, s[18:19]
	global_load_dwordx4 v[42:45], v[20:21], off
	v_lshl_add_u64 v[20:21], v[20:21], 0, s[18:19]
	global_load_dwordx4 v[46:49], v[20:21], off
	v_lshl_add_u64 v[20:21], v[20:21], 0, s[18:19]
	global_load_dwordx4 v[50:53], v[20:21], off
	v_lshl_add_u64 v[20:21], v[20:21], 0, s[18:19]
	global_load_dwordx4 v[54:57], v[20:21], off
	v_lshl_add_u64 v[20:21], v[20:21], 0, s[18:19]
	global_load_dwordx4 v[58:61], v[20:21], off
	v_lshl_add_u64 v[20:21], v[20:21], 0, s[18:19]
	global_load_dwordx4 v[62:65], v[20:21], off
	v_lshl_add_u64 v[20:21], v[20:21], 0, s[18:19]
	global_load_dwordx4 v[66:69], v[20:21], off
	v_lshl_add_u64 v[20:21], v[20:21], 0, s[18:19]
	ds_read_b32 v70, v16
	ds_read_b32 v86, v16 offset:8192
	ds_read_b32 v72, v16 offset:84
	ds_read_b32 v88, v16 offset:8276
	ds_read_b32 v74, v16 offset:168
	ds_read_b32 v90, v16 offset:8360
	ds_read_b32 v76, v16 offset:252
	ds_read_b32 v92, v16 offset:8444
	ds_read_b32 v78, v16 offset:336
	ds_read_b32 v94, v16 offset:8528
	ds_read_b32 v80, v16 offset:420
	ds_read_b32 v96, v16 offset:8612
	ds_read_b32 v82, v16 offset:504
	ds_read_b32 v98, v16 offset:8696
	ds_read_b32 v84, v16 offset:588
	ds_read_b32 v100, v16 offset:8780
	v_add_u32_e32 v16, 0x2a0, v16
	s_waitcnt lgkmcnt(0)
	s_waitcnt vmcnt(7)
	v_pk_fma_f32 v[4:5], v[32:33], v[70:71], v[4:5] op_sel_hi:[1,0,1]
	v_pk_fma_f32 v[2:3], v[30:31], v[70:71], v[2:3] op_sel_hi:[1,0,1]
	v_pk_fma_f32 v[8:9], v[32:33], v[86:87], v[8:9] op_sel_hi:[1,0,1]
	v_pk_fma_f32 v[6:7], v[30:31], v[86:87], v[6:7] op_sel_hi:[1,0,1]
	s_waitcnt vmcnt(6)
	v_pk_fma_f32 v[4:5], v[44:45], v[72:73], v[4:5] op_sel_hi:[1,0,1]
	v_pk_fma_f32 v[2:3], v[42:43], v[72:73], v[2:3] op_sel_hi:[1,0,1]
	v_pk_fma_f32 v[8:9], v[44:45], v[88:89], v[8:9] op_sel_hi:[1,0,1]
	v_pk_fma_f32 v[6:7], v[42:43], v[88:89], v[6:7] op_sel_hi:[1,0,1]
	s_waitcnt vmcnt(5)
	v_pk_fma_f32 v[4:5], v[48:49], v[74:75], v[4:5] op_sel_hi:[1,0,1]
	v_pk_fma_f32 v[2:3], v[46:47], v[74:75], v[2:3] op_sel_hi:[1,0,1]
	v_pk_fma_f32 v[8:9], v[48:49], v[90:91], v[8:9] op_sel_hi:[1,0,1]
	v_pk_fma_f32 v[6:7], v[46:47], v[90:91], v[6:7] op_sel_hi:[1,0,1]
	s_waitcnt vmcnt(4)
	v_pk_fma_f32 v[4:5], v[52:53], v[76:77], v[4:5] op_sel_hi:[1,0,1]
	v_pk_fma_f32 v[2:3], v[50:51], v[76:77], v[2:3] op_sel_hi:[1,0,1]
	v_pk_fma_f32 v[8:9], v[52:53], v[92:93], v[8:9] op_sel_hi:[1,0,1]
	v_pk_fma_f32 v[6:7], v[50:51], v[92:93], v[6:7] op_sel_hi:[1,0,1]
	s_waitcnt vmcnt(3)
	v_pk_fma_f32 v[4:5], v[56:57], v[78:79], v[4:5] op_sel_hi:[1,0,1]
	v_pk_fma_f32 v[2:3], v[54:55], v[78:79], v[2:3] op_sel_hi:[1,0,1]
	v_pk_fma_f32 v[8:9], v[56:57], v[94:95], v[8:9] op_sel_hi:[1,0,1]
	v_pk_fma_f32 v[6:7], v[54:55], v[94:95], v[6:7] op_sel_hi:[1,0,1]
	s_waitcnt vmcnt(2)
	v_pk_fma_f32 v[4:5], v[60:61], v[80:81], v[4:5] op_sel_hi:[1,0,1]
	v_pk_fma_f32 v[2:3], v[58:59], v[80:81], v[2:3] op_sel_hi:[1,0,1]
	v_pk_fma_f32 v[8:9], v[60:61], v[96:97], v[8:9] op_sel_hi:[1,0,1]
	v_pk_fma_f32 v[6:7], v[58:59], v[96:97], v[6:7] op_sel_hi:[1,0,1]
	s_waitcnt vmcnt(1)
	v_pk_fma_f32 v[4:5], v[64:65], v[82:83], v[4:5] op_sel_hi:[1,0,1]
	v_pk_fma_f32 v[2:3], v[62:63], v[82:83], v[2:3] op_sel_hi:[1,0,1]
	v_pk_fma_f32 v[8:9], v[64:65], v[98:99], v[8:9] op_sel_hi:[1,0,1]
	v_pk_fma_f32 v[6:7], v[62:63], v[98:99], v[6:7] op_sel_hi:[1,0,1]
	s_waitcnt vmcnt(0)
	v_pk_fma_f32 v[4:5], v[68:69], v[84:85], v[4:5] op_sel_hi:[1,0,1]
	v_pk_fma_f32 v[2:3], v[66:67], v[84:85], v[2:3] op_sel_hi:[1,0,1]
	v_pk_fma_f32 v[8:9], v[68:69], v[100:101], v[8:9] op_sel_hi:[1,0,1]
	v_pk_fma_f32 v[6:7], v[66:67], v[100:101], v[6:7] op_sel_hi:[1,0,1]
	s_sub_i32 s10, s10, 1
	s_cmp_lg_u32 s10, 0
	s_cbranch_scc1 .Lgemv_blk
	v_add_u32_e32 v28, 0x7e0, v28
